# W_in weight transpose (phase 0): both tiles' row loads of a trip issued before the first tile's wait (4 loads in flight instead of 2)
# baseline (speedup 1.0000x reference)
; #define LAS __attribute__((address_space(3)))
; template <int MODE> DI void transpose_job(LAS unsigned char* lds, const float* src, int K, int N, bf16_t* dst, int bid, int nblk) {
;     ...
;     for (int t0 = bid; t0 < ntile; t0 += 2 * nblk) {
; #pragma unroll
;         for (int q = 0; q < 2; ++q) { const int t = t0 + q * nblk; LAS float* tl = (LAS float*)(lds + q * 16640);
;             if (t < ntile) { const int k0 = (t / tn) * 64, n0 = (t % tn) * 64;
; #pragma unroll
;                 for (int i = 0; i < 2; ++i) { const int kk = (tid >> 4) + 32 * i, nn = (tid & 15) * 4;
;                     f32x4 v = {0.f, 0.f, 0.f, 0.f}; if (n0 + nn < N) v = *(const f32x4*)(src + (size_t)(k0 + kk) * N + n0 + nn);
;                     tl[kk * 65 + nn] = v[0]; tl[kk * 65 + nn + 1] = v[1]; tl[kk * 65 + nn + 2] = v[2]; tl[kk * 65 + nn + 3] = v[3]; } } }
.LBB0_1333:
	s_or_b64 exec, exec, s[2:3]
	s_add_i32 s24, s20, s86
	s_cmpk_lt_i32 s24, 0x1220
	s_cselect_b64 s[2:3], -1, 0
	s_mul_hi_i32 s26, s24, 0xe1fc780f
	v_mov_b32_e32 v60, 0
	v_mov_b32_e32 v61, 0
	v_mov_b32_e32 v62, 0
	v_mov_b32_e32 v63, 0
	v_mov_b32_e32 v64, 0
	v_mov_b32_e32 v65, 0
	v_mov_b32_e32 v66, 0
	v_mov_b32_e32 v67, 0
	s_cmpk_gt_i32 s24, 0x121f
	s_cbranch_scc1 .Ltrw_q0
	s_add_i32 s5, s26, s24
	s_lshr_b32 s20, s5, 31
	s_ashr_i32 s5, s5, 7
	s_add_i32 s5, s5, s20
	s_mul_i32 s20, s5, 0x91
	s_sub_i32 s20, s24, s20
	s_lshl_b32 s22, s20, 6
	v_or_b32_e32 v68, s22, v16
	v_cmp_gt_i32_e32 vcc, s34, v68
	s_and_saveexec_b64 s[20:21], vcc
	s_cbranch_execz .Ltrw_q1e
	s_ashr_i32 s23, s22, 31
	s_lshl_b32 s5, s5, 6
	v_lshl_add_u64 v[70:71], s[22:23], 2, v[0:1]
	v_add_u32_e32 v68, s5, v13
	v_mad_i64_i32 v[72:73], s[22:23], v68, s35, v[70:71]
	v_add_u32_e32 v68, s5, v19
	v_mad_i64_i32 v[70:71], s[22:23], v68, s35, v[70:71]
	global_load_dwordx4 v[60:63], v[72:73], off
	s_nop 0
	global_load_dwordx4 v[64:67], v[70:71], off

; #define LAS __attribute__((address_space(3)))
; template <int MODE> DI void transpose_job(LAS unsigned char* lds, const float* src, int K, int N, bf16_t* dst, int bid, int nblk) {
;     ...
;     for (int t0 = bid; t0 < ntile; t0 += 2 * nblk) {
; #pragma unroll
;         for (int q = 0; q < 2; ++q) { const int t = t0 + q * nblk; LAS float* tl = (LAS float*)(lds + q * 16640);
;             if (t < ntile) { const int k0 = (t / tn) * 64, n0 = (t % tn) * 64;
; #pragma unroll
;                 for (int i = 0; i < 2; ++i) { const int kk = (tid >> 4) + 32 * i, nn = (tid & 15) * 4;
;                     f32x4 v = {0.f, 0.f, 0.f, 0.f}; if (n0 + nn < N) v = *(const f32x4*)(src + (size_t)(k0 + kk) * N + n0 + nn);
;                     tl[kk * 65 + nn] = v[0]; tl[kk * 65 + nn + 1] = v[1]; tl[kk * 65 + nn + 2] = v[2]; tl[kk * 65 + nn + 3] = v[3]; } } }
.Ltrw_q0:
	v_add_u32_e32 v2, 0x2080, v21
	s_waitcnt vmcnt(1)
	ds_write2_b32 v21, v8, v9 offset1:1
	ds_write2_b32 v21, v10, v11 offset0:2 offset1:3
	s_waitcnt vmcnt(0)
	ds_write2_b32 v2, v4, v5 offset1:1
	v_add_u32_e32 v2, 0x2088, v21
	ds_write2_b32 v2, v6, v7 offset1:1
	s_cmpk_gt_i32 s24, 0x121f
	s_cbranch_scc1 .LBB0_1337
	v_add_u32_e32 v2, 0x4100, v21
	ds_write2_b32 v2, v60, v61 offset1:1
	v_add_u32_e32 v2, 0x4108, v21
	ds_write2_b32 v2, v62, v63 offset1:1
	v_add_u32_e32 v2, 0x6180, v21
	ds_write2_b32 v2, v64, v65 offset1:1
	v_add_u32_e32 v2, 0x6188, v21
	ds_write2_b32 v2, v66, v67 offset1:1
